# v65 + GEMM-tail partial-sum reduction loops de-serialized: 5-8 ds_reads in flight with counted lgkmcnt instead of 112 serialized round trips
# speedup vs baseline: 1.0089x; 1.0089x over previous
;     __device__ __forceinline__ void run(const f32x4 (&acc)[2][2][4][2], const Unit& u, int wr, int wc, int fr, int fq, const int nai, LAS unsigned char* lds, const int ui) const {
;     ...
;         const int pn = u.pn; const bool isqk = pn < 4;
;         f32x4 gv[2][2];
; #pragma unroll
;         for (int bj = 0; bj < 2; ++bj)
; #pragma unroll
;             for (int n = 0; n < 2; ++n) gv[bj][n] = isqk ? *(const f32x4*)((pn < 2 ? gq : gk) + 32 * bj + 8 * fq + 4 * n) : (f32x4){1.f, 1.f, 1.f, 1.f};
;         const float qs = (pn < 2) ? C2 : 1.f;
; template <class Epi, int K>
; __device__ __forceinline__ void gemm_tail(LAS unsigned char* lds, const bf16_t* A, const bf16_t* Bt, const int N, const Epi& E, const int bid, const int G, const int tid_in) {
;     ...
;             for (int w = 1; w < 8; ++w) {
; #pragma unroll
;                 for (int bj = 0; bj < 2; ++bj)
; #pragma unroll
;                     for (int m = 0; m < 4; ++m)
; #pragma unroll
;                         for (int n = 0; n < 2; ++n) full[0][bj][m][n] += P[(w * 16 + bj * 8 + m * 2 + n) * 64 + lane];
;                 asm volatile("" ::: "memory");
;             }
.LBB0_326:
	v_add_u32_e32 v0, s11, v210
	s_addk_i32 s11, 0x4000
	s_cmp_lg_u32 s11, 0x20000
	ds_read_b128 v[34:37], v0
	ds_read_b128 v[38:41], v0 offset:1024
	ds_read_b128 v[42:45], v0 offset:2048
	ds_read_b128 v[46:49], v0 offset:3072
	ds_read_b128 v[186:189], v0 offset:4096
	ds_read_b128 v[202:205], v0 offset:5120
	ds_read_b128 v[224:227], v0 offset:6144
	ds_read_b128 v[228:231], v0 offset:7168
	s_waitcnt lgkmcnt(7)
	v_pk_add_f32 v[72:73], v[72:73], v[36:37]
	v_pk_add_f32 v[70:71], v[70:71], v[34:35]
	ds_read_b128 v[34:37], v0 offset:8192
	s_waitcnt lgkmcnt(7)
	v_pk_add_f32 v[68:69], v[68:69], v[40:41]
	v_pk_add_f32 v[66:67], v[66:67], v[38:39]
	ds_read_b128 v[38:41], v0 offset:9216
	s_waitcnt lgkmcnt(7)
	v_pk_add_f32 v[56:57], v[56:57], v[44:45]
	v_pk_add_f32 v[54:55], v[54:55], v[42:43]
	ds_read_b128 v[42:45], v0 offset:10240
	s_waitcnt lgkmcnt(7)
	v_pk_add_f32 v[52:53], v[52:53], v[48:49]
	v_pk_add_f32 v[50:51], v[50:51], v[46:47]
	ds_read_b128 v[46:49], v0 offset:11264
	s_waitcnt lgkmcnt(7)
	v_pk_add_f32 v[24:25], v[24:25], v[188:189]
	v_pk_add_f32 v[22:23], v[22:23], v[186:187]
	ds_read_b128 v[186:189], v0 offset:12288
	s_waitcnt lgkmcnt(7)
	v_pk_add_f32 v[20:21], v[20:21], v[204:205]
	v_pk_add_f32 v[18:19], v[18:19], v[202:203]
	ds_read_b128 v[202:205], v0 offset:13312
	s_waitcnt lgkmcnt(7)
	v_pk_add_f32 v[8:9], v[8:9], v[226:227]
	v_pk_add_f32 v[6:7], v[6:7], v[224:225]
	ds_read_b128 v[224:227], v0 offset:14336
	s_waitcnt lgkmcnt(7)
	v_pk_add_f32 v[4:5], v[4:5], v[230:231]
	v_pk_add_f32 v[2:3], v[2:3], v[228:229]
	ds_read_b128 v[228:231], v0 offset:15360
	s_waitcnt lgkmcnt(7)
	v_pk_add_f32 v[76:77], v[76:77], v[36:37]
	v_pk_add_f32 v[74:75], v[74:75], v[34:35]
	s_waitcnt lgkmcnt(6)
	v_pk_add_f32 v[80:81], v[80:81], v[40:41]
	v_pk_add_f32 v[78:79], v[78:79], v[38:39]
	s_waitcnt lgkmcnt(5)
	v_pk_add_f32 v[64:65], v[64:65], v[44:45]
	v_pk_add_f32 v[62:63], v[62:63], v[42:43]
	s_waitcnt lgkmcnt(4)
	v_pk_add_f32 v[60:61], v[60:61], v[48:49]
	v_pk_add_f32 v[58:59], v[58:59], v[46:47]
	s_waitcnt lgkmcnt(3)
	v_pk_add_f32 v[32:33], v[32:33], v[188:189]
	v_pk_add_f32 v[30:31], v[30:31], v[186:187]
	s_waitcnt lgkmcnt(2)
	v_pk_add_f32 v[28:29], v[28:29], v[204:205]
	v_pk_add_f32 v[26:27], v[26:27], v[202:203]
	s_waitcnt lgkmcnt(1)
	v_pk_add_f32 v[16:17], v[16:17], v[226:227]
	v_pk_add_f32 v[14:15], v[14:15], v[224:225]
	s_waitcnt lgkmcnt(0)
	v_pk_add_f32 v[12:13], v[12:13], v[230:231]
	v_pk_add_f32 v[10:11], v[10:11], v[228:229]
	s_cbranch_scc1 .LBB0_326
	s_cmp_lt_i32 s6, 4
	s_cselect_b64 s[14:15], -1, 0
	s_cmp_lt_i32 s6, 2
	v_mov_b32_e32 v42, 1.0
	s_cselect_b64 s[40:41], -1, 0
	s_cmp_gt_i32 s6, 3
	v_lshlrev_b32_e32 v0, 2, v82
	v_mov_b32_e32 v46, 1.0
	v_mov_b32_e32 v47, v42
	v_mov_b32_e32 v48, 1.0
	v_mov_b32_e32 v49, 1.0
	s_cbranch_scc1 .LBB0_329
	s_and_b64 s[20:21], s[40:41], exec
	s_cselect_b32 s21, s59, s61
	s_cselect_b32 s20, s58, s60
	global_load_dwordx4 v[46:49], v0, s[20:21]

;     __device__ __forceinline__ void run(const f32x4 (&acc)[2][2][4][2], const Unit& u, int wr, int wc, int fr, int fq, const int nai, LAS unsigned char* lds, const int ui) const {
;         const int pn = u.pn, col = pn * 256 + wc * 64 + 8 * fq;
; #pragma unroll
;         for (int ai = 0; ai < nai; ++ai) {
;             if (u.pm * 256 + ai * 128 + wr * 64 >= MROWS) continue;
;             u32x4 pre[4][2];
; #pragma unroll
;             for (int m = 0; m < 4; ++m) {
;                 const int r = u.pm * 256 + ai * 128 + wr * 64 + m * 16 + fr;
; #pragma unroll
;                 for (int bj = 0; bj < 2; ++bj) pre[m][bj] = *(const u32x4*)(HB + (size_t)r * DM + col + 32 * bj);
;             }
; #pragma unroll
;             for (int m = 0; m < 4; ++m) {
;                 const int r = u.pm * 256 + ai * 128 + wr * 64 + m * 16 + fr;
;                 int b, t; row_bt(r, b, t);
;                 float ss = 0.f;
; #pragma unroll
;                 for (int bj = 0; bj < 2; ++bj) {
;                     const u32x4 pw = pre[m][bj];
;                     const f32x4 b0 = {__uint_as_float(pw[0] << 16), __uint_as_float(pw[0] & 0xffff0000u), __uint_as_float(pw[1] << 16), __uint_as_float(pw[1] & 0xffff0000u)};
;                     const f32x4 b1 = {__uint_as_float(pw[2] << 16), __uint_as_float(pw[2] & 0xffff0000u), __uint_as_float(pw[3] << 16), __uint_as_float(pw[3] & 0xffff0000u)};
;                     const f32x4 h0 = b0 + acc[ai][bj][m][0], h1 = b1 + acc[ai][bj][m][1];
;                     if (final) { if (t >= 16) { float* op = out + (size_t)(b * SEQ + t - 16) * DM + col + 32 * bj; *(f32x4*)op = h0; *(f32x4*)(op + 4) = h1; } }
;                     else {
; template <class Epi, int K>
; __device__ __forceinline__ void gemm_tail(LAS unsigned char* lds, const bf16_t* A, const bf16_t* Bt, const int N, const Epi& E, const int bid, const int G, const int tid_in) {
;     ...
;             for (int w = 1; w < 8; ++w) {
; #pragma unroll
;                 for (int bj = 0; bj < 2; ++bj)
; #pragma unroll
;                     for (int m = 0; m < 4; ++m)
; #pragma unroll
;                         for (int n = 0; n < 2; ++n) full[0][bj][m][n] += P[(w * 16 + bj * 8 + m * 2 + n) * 64 + lane];
;                 asm volatile("" ::: "memory");
;             }
.LBB0_709:
	v_add_u32_e32 v54, s8, v144
	s_addk_i32 s8, 0x4000
	s_cmp_lg_u32 s8, 0x20000
	ds_read_b128 v[50:53], v54
	ds_read_b128 v[84:87], v54 offset:1024
	ds_read_b128 v[146:149], v54 offset:2048
	ds_read_b128 v[150:153], v54 offset:3072
	ds_read_b128 v[158:161], v54 offset:4096
	s_waitcnt lgkmcnt(4)
	v_pk_add_f32 v[60:61], v[60:61], v[52:53]
	v_pk_add_f32 v[58:59], v[58:59], v[50:51]
	ds_read_b128 v[50:53], v54 offset:5120
	s_waitcnt lgkmcnt(4)
	v_pk_add_f32 v[64:65], v[64:65], v[86:87]
	v_pk_add_f32 v[62:63], v[62:63], v[84:85]
	ds_read_b128 v[84:87], v54 offset:6144
	s_waitcnt lgkmcnt(4)
	v_pk_add_f32 v[40:41], v[40:41], v[148:149]
	v_pk_add_f32 v[38:39], v[38:39], v[146:147]
	ds_read_b128 v[146:149], v54 offset:7168
	s_waitcnt lgkmcnt(4)
	v_pk_add_f32 v[36:37], v[36:37], v[152:153]
	v_pk_add_f32 v[34:35], v[34:35], v[150:151]
	ds_read_b128 v[150:153], v54 offset:8192
	s_waitcnt lgkmcnt(4)
	v_pk_add_f32 v[24:25], v[24:25], v[160:161]
	v_pk_add_f32 v[22:23], v[22:23], v[158:159]
	ds_read_b128 v[158:161], v54 offset:9216
	s_waitcnt lgkmcnt(4)
	v_pk_add_f32 v[20:21], v[20:21], v[52:53]
	v_pk_add_f32 v[18:19], v[18:19], v[50:51]
	ds_read_b128 v[50:53], v54 offset:10240
	s_waitcnt lgkmcnt(4)
	v_pk_add_f32 v[8:9], v[8:9], v[86:87]
	v_pk_add_f32 v[6:7], v[6:7], v[84:85]
	ds_read_b128 v[84:87], v54 offset:11264
	s_waitcnt lgkmcnt(4)
	v_pk_add_f32 v[4:5], v[4:5], v[148:149]
	v_pk_add_f32 v[2:3], v[2:3], v[146:147]
	ds_read_b128 v[146:149], v54 offset:12288
	s_waitcnt lgkmcnt(4)
	v_pk_add_f32 v[72:73], v[72:73], v[152:153]
	v_pk_add_f32 v[70:71], v[70:71], v[150:151]
	ds_read_b128 v[150:153], v54 offset:13312
	s_waitcnt lgkmcnt(4)
	v_pk_add_f32 v[80:81], v[80:81], v[160:161]
	v_pk_add_f32 v[78:79], v[78:79], v[158:159]
	ds_read_b128 v[158:161], v54 offset:14336
	s_waitcnt lgkmcnt(4)
	v_pk_add_f32 v[48:49], v[48:49], v[52:53]
	v_pk_add_f32 v[46:47], v[46:47], v[50:51]
	ds_read_b128 v[50:53], v54 offset:15360
	s_waitcnt lgkmcnt(4)
	v_pk_add_f32 v[44:45], v[44:45], v[86:87]
	v_pk_add_f32 v[42:43], v[42:43], v[84:85]
	s_waitcnt lgkmcnt(3)
	v_pk_add_f32 v[32:33], v[32:33], v[148:149]
	v_pk_add_f32 v[30:31], v[30:31], v[146:147]
	s_waitcnt lgkmcnt(2)
	v_pk_add_f32 v[28:29], v[28:29], v[152:153]
	v_pk_add_f32 v[26:27], v[26:27], v[150:151]
	s_waitcnt lgkmcnt(1)
	v_pk_add_f32 v[16:17], v[16:17], v[160:161]
	v_pk_add_f32 v[14:15], v[14:15], v[158:159]
	s_waitcnt lgkmcnt(0)
	v_pk_add_f32 v[12:13], v[12:13], v[52:53]
	v_pk_add_f32 v[10:11], v[10:11], v[50:51]
	s_cbranch_scc1 .LBB0_709
	v_or_b32_e32 v140, s6, v142
	v_ashrrev_i32_e32 v141, 31, v140
	v_lshlrev_b64 v[154:155], 1, v[140:141]
	v_lshl_add_u64 v[50:51], s[18:19], 0, v[154:155]
	v_lshl_add_u64 v[52:53], v[50:51], 0, v[0:1]
	global_load_dwordx4 v[146:149], v[52:53], off
	global_load_dwordx4 v[150:153], v[52:53], off offset:64
	v_lshl_add_u64 v[52:53], v[50:51], 0, v[94:95]
	global_load_dwordx4 v[86:89], v[52:53], off
	global_load_dwordx4 v[82:85], v[52:53], off offset:64
	v_lshl_add_u64 v[52:53], v[50:51], 0, v[96:97]
	v_lshl_add_u64 v[50:51], v[50:51], 0, v[98:99]
	global_load_dwordx4 v[74:77], v[52:53], off
	global_load_dwordx4 v[66:69], v[52:53], off offset:64
	global_load_dwordx4 v[54:57], v[50:51], off
	s_nop 0
	global_load_dwordx4 v[50:53], v[50:51], off offset:64
	s_and_b32 s8, s3, -4
	s_ashr_i32 s9, s8, 31
	s_waitcnt vmcnt(7)
	v_lshlrev_b32_e32 v156, 16, v146
	v_and_b32_e32 v157, 0xffff0000, v146
	v_lshlrev_b32_e32 v146, 16, v147
	v_and_b32_e32 v147, 0xffff0000, v147
	v_pk_add_f32 v[60:61], v[60:61], v[146:147]
	v_pk_add_f32 v[58:59], v[58:59], v[156:157]
	v_lshlrev_b32_e32 v158, 16, v148
	v_and_b32_e32 v159, 0xffff0000, v148
	v_mul_f32_e32 v145, v59, v59
	v_mul_f32_e32 v146, v61, v61
	v_lshlrev_b32_e32 v148, 16, v149
	v_and_b32_e32 v149, 0xffff0000, v149
	v_pk_add_f32 v[62:63], v[62:63], v[158:159]
	v_fmac_f32_e32 v145, v58, v58
	v_fmac_f32_e32 v146, v60, v60
	v_pk_add_f32 v[64:65], v[64:65], v[148:149]
	v_add_f32_e32 v145, v145, v146
	v_mul_f32_e32 v146, v63, v63
	v_fmac_f32_e32 v146, v62, v62
	v_cvt_pk_bf16_f32 v58, v58, v59
	v_cvt_pk_bf16_f32 v59, v60, v61
	v_cvt_pk_bf16_f32 v60, v62, v63
	v_cvt_pk_bf16_f32 v61, v64, v65
	v_lshl_add_u64 v[62:63], v[124:125], 0, v[154:155]
	global_store_dwordx4 v[62:63], v[58:61], off
	v_add_f32_e32 v145, v146, v145
	v_mul_f32_e32 v146, v65, v65
	s_waitcnt vmcnt(7)
	v_lshlrev_b32_e32 v58, 16, v150
	v_and_b32_e32 v59, 0xffff0000, v150
	v_lshlrev_b32_e32 v60, 16, v151
	v_and_b32_e32 v61, 0xffff0000, v151
	v_pk_add_f32 v[60:61], v[72:73], v[60:61]
	v_pk_add_f32 v[58:59], v[70:71], v[58:59]
	v_fmac_f32_e32 v146, v64, v64
	v_lshlrev_b32_e32 v64, 16, v152
	v_and_b32_e32 v65, 0xffff0000, v152
	v_mul_f32_e32 v72, v59, v59
	v_mul_f32_e32 v73, v61, v61
	v_add_f32_e32 v145, v146, v145
	v_lshlrev_b32_e32 v146, 16, v153
	v_and_b32_e32 v147, 0xffff0000, v153
	v_pk_add_f32 v[64:65], v[78:79], v[64:65]
	v_fmac_f32_e32 v72, v58, v58
	v_fmac_f32_e32 v73, v60, v60
	v_pk_add_f32 v[70:71], v[80:81], v[146:147]
	v_add_f32_e32 v72, v72, v73
	v_mul_f32_e32 v73, v65, v65
	v_fmac_f32_e32 v73, v64, v64
	v_cvt_pk_bf16_f32 v58, v58, v59
	v_cvt_pk_bf16_f32 v59, v60, v61
	v_cvt_pk_bf16_f32 v60, v64, v65
	v_cvt_pk_bf16_f32 v61, v70, v71
	v_add_f32_e32 v72, v73, v72
	v_mul_f32_e32 v73, v71, v71
	global_store_dwordx4 v[62:63], v[58:61], off offset:64
	v_fmac_f32_e32 v73, v70, v70
	v_add_f32_e32 v72, v73, v72
	v_xor_b32_e32 v58, 16, v215
	v_cmp_lt_i32_e32 vcc, v58, v217
	v_add_f32_e32 v72, v145, v72
	s_nop 0
	v_cndmask_b32_e32 v58, v215, v58, vcc
	v_lshlrev_b32_e32 v58, 2, v58
	ds_bpermute_b32 v59, v58, v72
	s_waitcnt lgkmcnt(0)
	v_add_f32_e32 v60, v72, v59
	v_xor_b32_e32 v59, 32, v215
	v_cmp_lt_i32_e32 vcc, v59, v217
	s_nop 1
	v_cndmask_b32_e32 v59, v215, v59, vcc
	v_lshlrev_b32_e32 v59, 2, v59
	ds_bpermute_b32 v61, v59, v60
	s_and_saveexec_b64 s[10:11], s[40:41]
	s_cbranch_execz .LBB0_712
	v_lshl_add_u64 v[62:63], s[8:9], 2, v[126:127]
	s_lshl_b32 s6, s14, 2
	v_lshl_add_u64 v[62:63], v[62:63], 0, s[6:7]
	s_waitcnt lgkmcnt(0)
	v_add_f32_e32 v60, v60, v61
	global_store_dword v[62:63], v60, off

; #define LAS __attribute__((address_space(3)))
; __device__ __forceinline__ u32x4 pack8(const f32x4 a, const f32x4 b) { u32x4 w; w.x = cvtpk(a[0], a[1]); w.y = cvtpk(a[2], a[3]); w.z = cvtpk(b[0], b[1]); w.w = cvtpk(b[2], b[3]); return w; }
;     __device__ __forceinline__ void run(const f32x4 (&acc)[2][2][4][2], const Unit& u, int wr, int wc, int fr, int fq, const int nai, LAS unsigned char* lds, const int ui) const {
;         const LAS float* RT = (const LAS float*)(lds + LDS_RSTAB) + (ui & 1) * 256;
; #pragma unroll
;         for (int ai = 0; ai < nai; ++ai)
; #pragma unroll
;             for (int m = 0; m < 4; ++m) {
;                 const int r = u.pm * 256 + ai * 128 + wr * 64 + m * 16 + fr;
;                 const float rs = RT[ai * 128 + wr * 64 + m * 16 + fr];
;                 f32x4 a[2];
; #pragma unroll
;                 for (int n = 0; n < 2; ++n) {
;                     const f32x4 g = acc[ai][0][m][n] * rs, uu = acc[ai][1][m][n] * rs;
; #pragma unroll
;                     for (int i = 0; i < 4; ++i) a[n][i] = g[i] * uu[i] * __builtin_amdgcn_rcpf(1.0f + __expf(-g[i]));
;                 }
;                 *(u32x4*)(ACT + (size_t)r * DFF + u.pn * 128 + wc * 32 + 8 * fq) = pack8(a[0], a[1]);
; template <class Epi, int K>
; __device__ __forceinline__ void gemm_tail(LAS unsigned char* lds, const bf16_t* A, const bf16_t* Bt, const int N, const Epi& E, const int bid, const int G, const int tid_in) {
;     ...
;             for (int w = 1; w < 8; ++w) {
; #pragma unroll
;                 for (int bj = 0; bj < 2; ++bj)
; #pragma unroll
;                     for (int m = 0; m < 4; ++m)
; #pragma unroll
;                         for (int n = 0; n < 2; ++n) full[0][bj][m][n] += P[(w * 16 + bj * 8 + m * 2 + n) * 64 + lane];
;                 asm volatile("" ::: "memory");
;             }
.LBB0_797:
	v_add_u32_e32 v109, s8, v107
	s_addk_i32 s8, 0x4000
	s_cmp_lg_u32 s8, 0x20000
	ds_read_b128 v[110:113], v109
	ds_read_b128 v[118:121], v109 offset:1024
	ds_read_b128 v[122:125], v109 offset:2048
	ds_read_b128 v[126:129], v109 offset:3072
	ds_read_b128 v[130:133], v109 offset:4096
	ds_read_b128 v[134:137], v109 offset:5120
	ds_read_b128 v[138:141], v109 offset:6144
	ds_read_b128 v[142:145], v109 offset:7168
	s_waitcnt lgkmcnt(7)
	v_pk_add_f32 v[56:57], v[56:57], v[112:113]
	v_pk_add_f32 v[54:55], v[54:55], v[110:111]
	ds_read_b128 v[110:113], v109 offset:8192
	s_waitcnt lgkmcnt(7)
	v_pk_add_f32 v[48:49], v[48:49], v[120:121]
	v_pk_add_f32 v[46:47], v[46:47], v[118:119]
	ds_read_b128 v[118:121], v109 offset:9216
	s_waitcnt lgkmcnt(7)
	v_pk_add_f32 v[40:41], v[40:41], v[124:125]
	v_pk_add_f32 v[38:39], v[38:39], v[122:123]
	ds_read_b128 v[122:125], v109 offset:10240
	s_waitcnt lgkmcnt(7)
	v_pk_add_f32 v[36:37], v[36:37], v[128:129]
	v_pk_add_f32 v[34:35], v[34:35], v[126:127]
	ds_read_b128 v[126:129], v109 offset:11264
	s_waitcnt lgkmcnt(7)
	v_pk_add_f32 v[24:25], v[24:25], v[132:133]
	v_pk_add_f32 v[22:23], v[22:23], v[130:131]
	ds_read_b128 v[130:133], v109 offset:12288
	s_waitcnt lgkmcnt(7)
	v_pk_add_f32 v[16:17], v[16:17], v[136:137]
	v_pk_add_f32 v[14:15], v[14:15], v[134:135]
	ds_read_b128 v[134:137], v109 offset:13312
	s_waitcnt lgkmcnt(7)
	v_pk_add_f32 v[8:9], v[8:9], v[140:141]
	v_pk_add_f32 v[6:7], v[6:7], v[138:139]
	ds_read_b128 v[138:141], v109 offset:14336
	s_waitcnt lgkmcnt(7)
	v_pk_add_f32 v[4:5], v[4:5], v[144:145]
	v_pk_add_f32 v[2:3], v[2:3], v[142:143]
	ds_read_b128 v[142:145], v109 offset:15360
	s_waitcnt lgkmcnt(7)
	v_pk_add_f32 v[60:61], v[60:61], v[112:113]
	v_pk_add_f32 v[58:59], v[58:59], v[110:111]
	s_waitcnt lgkmcnt(6)
	v_pk_add_f32 v[64:65], v[64:65], v[120:121]
	v_pk_add_f32 v[62:63], v[62:63], v[118:119]
	s_waitcnt lgkmcnt(5)
	v_pk_add_f32 v[52:53], v[52:53], v[124:125]
	v_pk_add_f32 v[50:51], v[50:51], v[122:123]
	s_waitcnt lgkmcnt(4)
	v_pk_add_f32 v[44:45], v[44:45], v[128:129]
	v_pk_add_f32 v[42:43], v[42:43], v[126:127]
	s_waitcnt lgkmcnt(3)
	v_pk_add_f32 v[32:33], v[32:33], v[132:133]
	v_pk_add_f32 v[30:31], v[30:31], v[130:131]
	s_waitcnt lgkmcnt(2)
	v_pk_add_f32 v[28:29], v[28:29], v[136:137]
	v_pk_add_f32 v[26:27], v[26:27], v[134:135]
	s_waitcnt lgkmcnt(1)
	v_pk_add_f32 v[20:21], v[20:21], v[140:141]
	v_pk_add_f32 v[18:19], v[18:19], v[138:139]
	s_waitcnt lgkmcnt(0)
	v_pk_add_f32 v[12:13], v[12:13], v[144:145]
	v_pk_add_f32 v[10:11], v[10:11], v[142:143]
	s_cbranch_scc1 .LBB0_797
	ds_read2_b32 v[110:111], v108 offset1:16
	s_lshl_b32 s8, s10, 7
	s_ashr_i32 s9, s8, 31
	s_lshl_b64 s[8:9], s[8:9], 1
	s_lshl_b32 s6, s6, 1
	s_waitcnt lgkmcnt(0)
	v_pk_mul_f32 v[54:55], v[54:55], v[110:111] op_sel_hi:[1,0]
	v_pk_mul_f32 v[58:59], v[58:59], v[110:111] op_sel_hi:[1,0]
	v_mul_f32_e32 v109, 0xbfb8aa3b, v54
	v_mul_f32_e32 v112, 0xbfb8aa3b, v55
	v_exp_f32_e32 v109, v109
	v_exp_f32_e32 v112, v112
	v_pk_mul_f32 v[56:57], v[56:57], v[110:111] op_sel_hi:[1,0]
	v_pk_mul_f32 v[54:55], v[54:55], v[58:59]
	v_add_f32_e32 v58, 1.0, v109
	v_add_f32_e32 v59, 1.0, v112
	v_mul_f32_e32 v109, 0xbfb8aa3b, v56
	v_mul_f32_e32 v112, 0xbfb8aa3b, v57
	v_rcp_f32_e32 v58, v58
	v_rcp_f32_e32 v59, v59
	v_exp_f32_e32 v109, v109
	v_exp_f32_e32 v112, v112
	v_pk_mul_f32 v[60:61], v[60:61], v[110:111] op_sel_hi:[1,0]
	v_pk_mul_f32 v[54:55], v[54:55], v[58:59]
	v_add_f32_e32 v58, 1.0, v109
	v_add_f32_e32 v59, 1.0, v112
	v_rcp_f32_e32 v58, v58
	v_rcp_f32_e32 v59, v59
	v_pk_mul_f32 v[46:47], v[46:47], v[110:111] op_sel_hi:[1,0]
	v_pk_mul_f32 v[56:57], v[56:57], v[60:61]
	v_mul_f32_e32 v109, 0xbfb8aa3b, v46
	v_pk_mul_f32 v[56:57], v[56:57], v[58:59]
	v_mul_f32_e32 v59, 0xbfb8aa3b, v47
	v_exp_f32_e32 v109, v109
	v_exp_f32_e32 v59, v59
	v_pk_mul_f32 v[60:61], v[62:63], v[110:111] op_sel_hi:[1,0]
	v_pk_mul_f32 v[48:49], v[48:49], v[110:111] op_sel_hi:[1,0]
	v_pk_mul_f32 v[46:47], v[46:47], v[60:61]
	v_mul_f32_e32 v60, 0xbfb8aa3b, v48
	v_mul_f32_e32 v61, 0xbfb8aa3b, v49
	v_exp_f32_e32 v60, v60
	v_exp_f32_e32 v61, v61
	v_add_f32_e32 v58, 1.0, v109
	v_add_f32_e32 v59, 1.0, v59
	v_rcp_f32_e32 v58, v58
	v_rcp_f32_e32 v59, v59
	v_add_f32_e32 v60, 1.0, v60
	v_add_f32_e32 v61, 1.0, v61
	v_rcp_f32_e32 v60, v60
	v_rcp_f32_e32 v61, v61
	v_pk_mul_f32 v[58:59], v[46:47], v[58:59]
	v_pk_mul_f32 v[46:47], v[64:65], v[110:111] op_sel_hi:[1,0]
	s_nop 0
	v_pk_mul_f32 v[46:47], v[48:49], v[46:47]
	v_cvt_pk_bf16_f32 v48, v58, v59
	v_pk_mul_f32 v[60:61], v[46:47], v[60:61]
	v_cvt_pk_bf16_f32 v46, v54, v55
	v_cvt_pk_bf16_f32 v47, v56, v57
	v_lshl_add_u64 v[54:55], v[72:73], 0, s[8:9]
	v_mov_b32_e32 v56, v111
	v_pk_mul_f32 v[38:39], v[38:39], v[56:57] op_sel_hi:[1,0]
	v_lshl_add_u64 v[54:55], v[54:55], 0, s[6:7]
	v_cvt_pk_bf16_f32 v49, v60, v61
	v_mul_f32_e32 v57, 0xbfb8aa3b, v38
	v_lshl_add_u64 v[54:55], v[54:55], 0, v[0:1]
	v_exp_f32_e32 v57, v57
	global_store_dwordx4 v[54:55], v[46:49], off
	v_pk_mul_f32 v[40:41], v[40:41], v[56:57] op_sel_hi:[1,0]
	s_nop 0
	v_mul_f32_e32 v47, 0xbfb8aa3b, v39
	v_exp_f32_e32 v47, v47
	v_pk_mul_f32 v[48:49], v[50:51], v[56:57] op_sel_hi:[1,0]
	v_add_f32_e32 v46, 1.0, v57
	v_pk_mul_f32 v[38:39], v[38:39], v[48:49]
	v_add_f32_e32 v47, 1.0, v47
	v_mul_f32_e32 v48, 0xbfb8aa3b, v40
	v_mul_f32_e32 v49, 0xbfb8aa3b, v41
	v_rcp_f32_e32 v46, v46
	v_rcp_f32_e32 v47, v47
	v_exp_f32_e32 v48, v48
	v_exp_f32_e32 v49, v49
	v_pk_mul_f32 v[34:35], v[34:35], v[56:57] op_sel_hi:[1,0]
	v_pk_mul_f32 v[38:39], v[38:39], v[46:47]
	v_add_f32_e32 v46, 1.0, v48
	v_add_f32_e32 v47, 1.0, v49
	v_rcp_f32_e32 v46, v46
	v_rcp_f32_e32 v47, v47
	v_mul_f32_e32 v48, 0xbfb8aa3b, v34
	v_exp_f32_e32 v50, v48
	v_pk_mul_f32 v[48:49], v[52:53], v[56:57] op_sel_hi:[1,0]
	v_pk_mul_f32 v[42:43], v[42:43], v[56:57] op_sel_hi:[1,0]
	v_pk_mul_f32 v[40:41], v[40:41], v[48:49]
	v_pk_mul_f32 v[36:37], v[36:37], v[56:57] op_sel_hi:[1,0]
	v_pk_mul_f32 v[40:41], v[40:41], v[46:47]
	v_mul_f32_e32 v47, 0xbfb8aa3b, v35
	v_exp_f32_e32 v47, v47
	v_pk_mul_f32 v[34:35], v[34:35], v[42:43]
	v_mul_f32_e32 v43, 0xbfb8aa3b, v36
	v_exp_f32_e32 v43, v43
	v_add_f32_e32 v42, 1.0, v47
	v_mul_f32_e32 v47, 0xbfb8aa3b, v37
	v_exp_f32_e32 v48, v47
	v_add_f32_e32 v46, 1.0, v50
	v_rcp_f32_e32 v46, v46
	v_rcp_f32_e32 v47, v42
	v_add_f32_e32 v42, 1.0, v43
	v_add_f32_e32 v43, 1.0, v48
	v_rcp_f32_e32 v42, v42
	v_rcp_f32_e32 v43, v43
	v_pk_mul_f32 v[46:47], v[34:35], v[46:47]
	v_pk_mul_f32 v[34:35], v[44:45], v[56:57] op_sel_hi:[1,0]
	s_nop 0
	v_pk_mul_f32 v[34:35], v[36:37], v[34:35]
	v_cvt_pk_bf16_f32 v36, v46, v47
	v_pk_mul_f32 v[42:43], v[34:35], v[42:43]
	v_cvt_pk_bf16_f32 v34, v38, v39
	ds_read2_b32 v[38:39], v108 offset0:32 offset1:48
	v_cvt_pk_bf16_f32 v35, v40, v41
	v_lshl_add_u64 v[40:41], v[74:75], 0, s[8:9]
	v_lshl_add_u64 v[40:41], v[40:41], 0, s[6:7]
	v_cvt_pk_bf16_f32 v37, v42, v43
	s_waitcnt lgkmcnt(0)
; __device__ __forceinline__ u32x4 pack8(const f32x4 a, const f32x4 b) { u32x4 w; w.x = cvtpk(a[0], a[1]); w.y = cvtpk(a[2], a[3]); w.z = cvtpk(b[0], b[1]); w.w = cvtpk(b[2], b[3]); return w; }
;     __device__ __forceinline__ void run(const f32x4 (&acc)[2][2][4][2], const Unit& u, int wr, int wc, int fr, int fq, const int nai, LAS unsigned char* lds, const int ui) const {
;     ...
;         for (int ai = 0; ai < nai; ++ai)
; #pragma unroll
;             for (int m = 0; m < 4; ++m) {
;                 const int r = u.pm * 256 + ai * 128 + wr * 64 + m * 16 + fr;
;                 const float rs = RT[ai * 128 + wr * 64 + m * 16 + fr];
;                 f32x4 a[2];
; #pragma unroll
;                 for (int n = 0; n < 2; ++n) {
;                     const f32x4 g = acc[ai][0][m][n] * rs, uu = acc[ai][1][m][n] * rs;
; #pragma unroll
;                     for (int i = 0; i < 4; ++i) a[n][i] = g[i] * uu[i] * __builtin_amdgcn_rcpf(1.0f + __expf(-g[i]));
;                 }
;                 *(u32x4*)(ACT + (size_t)r * DFF + u.pn * 128 + wc * 32 + 8 * fq) = pack8(a[0], a[1]);
	v_pk_mul_f32 v[22:23], v[22:23], v[38:39] op_sel_hi:[1,0]
	v_lshl_add_u64 v[40:41], v[40:41], 0, v[0:1]
	global_store_dwordx4 v[40:41], v[34:37], off
	v_pk_mul_f32 v[30:31], v[30:31], v[38:39] op_sel_hi:[1,0]
	v_mul_f32_e32 v42, 0xbfb8aa3b, v22
	v_mul_f32_e32 v35, 0xbfb8aa3b, v23
	v_exp_f32_e32 v35, v35
	v_pk_mul_f32 v[22:23], v[22:23], v[30:31]
	v_pk_mul_f32 v[24:25], v[24:25], v[38:39] op_sel_hi:[1,0]
	v_exp_f32_e32 v42, v42
	v_add_f32_e32 v30, 1.0, v35
	v_rcp_f32_e32 v35, v30
	v_mul_f32_e32 v30, 0xbfb8aa3b, v24
	v_mul_f32_e32 v31, 0xbfb8aa3b, v25
	v_exp_f32_e32 v30, v30
	v_exp_f32_e32 v31, v31
	v_add_f32_e32 v34, 1.0, v42
	v_pk_mul_f32 v[32:33], v[32:33], v[38:39] op_sel_hi:[1,0]
	v_add_f32_e32 v30, 1.0, v30
	v_add_f32_e32 v31, 1.0, v31
	v_rcp_f32_e32 v30, v30
	v_rcp_f32_e32 v31, v31
	v_rcp_f32_e32 v34, v34
	v_pk_mul_f32 v[14:15], v[14:15], v[38:39] op_sel_hi:[1,0]
	v_pk_mul_f32 v[24:25], v[24:25], v[32:33]
	v_pk_mul_f32 v[26:27], v[26:27], v[38:39] op_sel_hi:[1,0]
	v_pk_mul_f32 v[24:25], v[24:25], v[30:31]
	v_mul_f32_e32 v31, 0xbfb8aa3b, v15
	v_exp_f32_e32 v31, v31
	v_pk_mul_f32 v[22:23], v[22:23], v[34:35]
	v_mul_f32_e32 v34, 0xbfb8aa3b, v14
	v_exp_f32_e32 v34, v34
	v_pk_mul_f32 v[16:17], v[16:17], v[38:39] op_sel_hi:[1,0]
	v_pk_mul_f32 v[14:15], v[14:15], v[26:27]
	v_add_f32_e32 v26, 1.0, v31
	v_mul_f32_e32 v27, 0xbfb8aa3b, v16
	v_mul_f32_e32 v31, 0xbfb8aa3b, v17
	v_exp_f32_e32 v27, v27
	v_exp_f32_e32 v32, v31
	v_add_f32_e32 v30, 1.0, v34
	v_rcp_f32_e32 v30, v30
	v_rcp_f32_e32 v31, v26
	v_add_f32_e32 v26, 1.0, v27
	v_add_f32_e32 v27, 1.0, v32
	v_rcp_f32_e32 v26, v26
	v_rcp_f32_e32 v27, v27
	v_pk_mul_f32 v[30:31], v[14:15], v[30:31]
	v_pk_mul_f32 v[14:15], v[28:29], v[38:39] op_sel_hi:[1,0]
	s_nop 0
	v_pk_mul_f32 v[14:15], v[16:17], v[14:15]
	v_cvt_pk_bf16_f32 v16, v30, v31
	v_pk_mul_f32 v[26:27], v[14:15], v[26:27]
	v_cvt_pk_bf16_f32 v14, v22, v23
	v_cvt_pk_bf16_f32 v15, v24, v25
	v_lshl_add_u64 v[22:23], v[76:77], 0, s[8:9]
	v_mov_b32_e32 v24, v39
	v_pk_mul_f32 v[6:7], v[6:7], v[24:25] op_sel_hi:[1,0]
	v_lshl_add_u64 v[22:23], v[22:23], 0, s[6:7]
	v_cvt_pk_bf16_f32 v17, v26, v27
	v_mul_f32_e32 v25, 0xbfb8aa3b, v6
	v_lshl_add_u64 v[22:23], v[22:23], 0, v[0:1]
	v_exp_f32_e32 v25, v25
	global_store_dwordx4 v[22:23], v[14:17], off
	v_pk_mul_f32 v[8:9], v[8:9], v[24:25] op_sel_hi:[1,0]
	s_nop 0
	v_mul_f32_e32 v15, 0xbfb8aa3b, v7
	v_exp_f32_e32 v15, v15
	v_pk_mul_f32 v[16:17], v[18:19], v[24:25] op_sel_hi:[1,0]
	v_add_f32_e32 v14, 1.0, v25
	v_pk_mul_f32 v[6:7], v[6:7], v[16:17]
	v_add_f32_e32 v15, 1.0, v15
	v_mul_f32_e32 v16, 0xbfb8aa3b, v8
	v_mul_f32_e32 v17, 0xbfb8aa3b, v9
	v_rcp_f32_e32 v14, v14
	v_rcp_f32_e32 v15, v15
	v_exp_f32_e32 v16, v16
	v_exp_f32_e32 v17, v17
	v_pk_mul_f32 v[2:3], v[2:3], v[24:25] op_sel_hi:[1,0]
	v_pk_mul_f32 v[6:7], v[6:7], v[14:15]
	v_add_f32_e32 v14, 1.0, v16
	v_add_f32_e32 v15, 1.0, v17
	v_rcp_f32_e32 v14, v14
	v_rcp_f32_e32 v15, v15
	v_mul_f32_e32 v16, 0xbfb8aa3b, v2
	v_exp_f32_e32 v18, v16
	v_pk_mul_f32 v[16:17], v[20:21], v[24:25] op_sel_hi:[1,0]
	v_pk_mul_f32 v[10:11], v[10:11], v[24:25] op_sel_hi:[1,0]
	v_pk_mul_f32 v[8:9], v[8:9], v[16:17]
	v_pk_mul_f32 v[4:5], v[4:5], v[24:25] op_sel_hi:[1,0]
	v_pk_mul_f32 v[8:9], v[8:9], v[14:15]
	v_mul_f32_e32 v15, 0xbfb8aa3b, v3
	v_exp_f32_e32 v15, v15
	v_pk_mul_f32 v[2:3], v[2:3], v[10:11]
	v_mul_f32_e32 v11, 0xbfb8aa3b, v4
	v_exp_f32_e32 v11, v11
	v_add_f32_e32 v10, 1.0, v15
	v_mul_f32_e32 v15, 0xbfb8aa3b, v5
	v_exp_f32_e32 v16, v15
	v_add_f32_e32 v14, 1.0, v18
	v_rcp_f32_e32 v14, v14
	v_rcp_f32_e32 v15, v10
	v_add_f32_e32 v10, 1.0, v11
	v_add_f32_e32 v11, 1.0, v16
	v_rcp_f32_e32 v10, v10
	v_rcp_f32_e32 v11, v11
	v_pk_mul_f32 v[14:15], v[2:3], v[14:15]
	v_pk_mul_f32 v[2:3], v[12:13], v[24:25] op_sel_hi:[1,0]
	s_nop 0
	v_pk_mul_f32 v[2:3], v[4:5], v[2:3]
	v_cvt_pk_bf16_f32 v4, v14, v15
	v_pk_mul_f32 v[10:11], v[2:3], v[10:11]
	v_cvt_pk_bf16_f32 v2, v6, v7
	v_lshl_add_u64 v[6:7], v[78:79], 0, s[8:9]
	v_lshl_add_u64 v[6:7], v[6:7], 0, s[6:7]
	v_cvt_pk_bf16_f32 v3, v8, v9
	v_cvt_pk_bf16_f32 v5, v10, v11
	v_lshl_add_u64 v[6:7], v[6:7], 0, v[0:1]
	global_store_dwordx4 v[6:7], v[2:5], off
	s_branch .LBB0_792

;     __device__ __forceinline__ void run(const f32x4 (&acc)[2][2][4][2], const Unit& u, int wr, int wc, int fr, int fq, const int nai, LAS unsigned char* lds, const int ui) const {
;     ...
;             for (int m = 0; m < 4; ++m) {
;                 const int r = u.pm * 256 + ai * 128 + wr * 64 + m * 16 + fr;
; #pragma unroll
;                 for (int bj = 0; bj < 2; ++bj) pre[m][bj] = *(const u32x4*)(HB + (size_t)r * DM + col + 32 * bj);
;             }
; #pragma unroll
;             for (int m = 0; m < 4; ++m) {
;                 const int r = u.pm * 256 + ai * 128 + wr * 64 + m * 16 + fr;
;                 int b, t; row_bt(r, b, t);
;                 float ss = 0.f;
; #pragma unroll
;                 for (int bj = 0; bj < 2; ++bj) {
;                     const u32x4 pw = pre[m][bj];
;                     const f32x4 b0 = {__uint_as_float(pw[0] << 16), __uint_as_float(pw[0] & 0xffff0000u), __uint_as_float(pw[1] << 16), __uint_as_float(pw[1] & 0xffff0000u)};
;                     const f32x4 b1 = {__uint_as_float(pw[2] << 16), __uint_as_float(pw[2] & 0xffff0000u), __uint_as_float(pw[3] << 16), __uint_as_float(pw[3] & 0xffff0000u)};
;                     const f32x4 h0 = b0 + acc[ai][bj][m][0], h1 = b1 + acc[ai][bj][m][1];
;                     if (final) { if (t >= 16) { float* op = out + (size_t)(b * SEQ + t - 16) * DM + col + 32 * bj; *(f32x4*)op = h0; *(f32x4*)(op + 4) = h1; } }
;                     else {
;                         ss += (h0[0] * h0[0] + h0[1] * h0[1]) + (h0[2] * h0[2] + h0[3] * h0[3]) + (h1[0] * h1[0] + h1[1] * h1[1]) + (h1[2] * h1[2] + h1[3] * h1[3]);
;                         *(u32x4*)(HB + (size_t)r * DM + col + 32 * bj) = pack8(h0, h1); }
; template <class Epi, int K>
; __device__ __forceinline__ void gemm_tail(LAS unsigned char* lds, const bf16_t* A, const bf16_t* Bt, const int N, const Epi& E, const int bid, const int G, const int tid_in) {
;     ...
;             for (int w = 1; w < 8; ++w) {
; #pragma unroll
;                 for (int bj = 0; bj < 2; ++bj)
; #pragma unroll
;                     for (int m = 0; m < 4; ++m)
; #pragma unroll
;                         for (int n = 0; n < 2; ++n) full[0][bj][m][n] += P[(w * 16 + bj * 8 + m * 2 + n) * 64 + lane];
;                 asm volatile("" ::: "memory");
;             }
.LBB0_1012:
	v_add_u32_e32 v70, s8, v222
	s_addk_i32 s8, 0x4000
	s_cmp_lg_u32 s8, 0x20000
	ds_read_b128 v[66:69], v70
	ds_read_b128 v[72:75], v70 offset:1024
	ds_read_b128 v[80:83], v70 offset:2048
	ds_read_b128 v[84:87], v70 offset:3072
	ds_read_b128 v[88:91], v70 offset:4096
	ds_read_b128 v[92:95], v70 offset:5120
	ds_read_b128 v[228:231], v70 offset:6144
	ds_read_b128 v[232:235], v70 offset:7168
	s_waitcnt lgkmcnt(7)
	v_pk_add_f32 v[52:53], v[52:53], v[68:69]
	v_pk_add_f32 v[50:51], v[50:51], v[66:67]
	ds_read_b128 v[66:69], v70 offset:8192
	s_waitcnt lgkmcnt(7)
	v_pk_add_f32 v[48:49], v[48:49], v[74:75]
	v_pk_add_f32 v[46:47], v[46:47], v[72:73]
	ds_read_b128 v[72:75], v70 offset:9216
	s_waitcnt lgkmcnt(7)
	v_pk_add_f32 v[24:25], v[24:25], v[82:83]
	v_pk_add_f32 v[22:23], v[22:23], v[80:81]
	ds_read_b128 v[80:83], v70 offset:10240
	s_waitcnt lgkmcnt(7)
	v_pk_add_f32 v[20:21], v[20:21], v[86:87]
	v_pk_add_f32 v[18:19], v[18:19], v[84:85]
	ds_read_b128 v[84:87], v70 offset:11264
	s_waitcnt lgkmcnt(7)
	v_pk_add_f32 v[16:17], v[16:17], v[90:91]
	v_pk_add_f32 v[14:15], v[14:15], v[88:89]
	ds_read_b128 v[88:91], v70 offset:12288
	s_waitcnt lgkmcnt(7)
	v_pk_add_f32 v[12:13], v[12:13], v[94:95]
	v_pk_add_f32 v[10:11], v[10:11], v[92:93]
	ds_read_b128 v[92:95], v70 offset:13312
	s_waitcnt lgkmcnt(7)
	v_pk_add_f32 v[8:9], v[8:9], v[230:231]
	v_pk_add_f32 v[6:7], v[6:7], v[228:229]
	ds_read_b128 v[228:231], v70 offset:14336
	s_waitcnt lgkmcnt(7)
	v_pk_add_f32 v[4:5], v[4:5], v[234:235]
	v_pk_add_f32 v[2:3], v[2:3], v[232:233]
	ds_read_b128 v[232:235], v70 offset:15360
	s_waitcnt lgkmcnt(7)
	v_pk_add_f32 v[40:41], v[40:41], v[68:69]
	v_pk_add_f32 v[38:39], v[38:39], v[66:67]
	s_waitcnt lgkmcnt(6)
	v_pk_add_f32 v[64:65], v[64:65], v[74:75]
	v_pk_add_f32 v[62:63], v[62:63], v[72:73]
	s_waitcnt lgkmcnt(5)
	v_pk_add_f32 v[60:61], v[60:61], v[82:83]
	v_pk_add_f32 v[58:59], v[58:59], v[80:81]
	s_waitcnt lgkmcnt(4)
	v_pk_add_f32 v[56:57], v[56:57], v[86:87]
	v_pk_add_f32 v[54:55], v[54:55], v[84:85]
	s_waitcnt lgkmcnt(3)
	v_pk_add_f32 v[44:45], v[44:45], v[90:91]
	v_pk_add_f32 v[42:43], v[42:43], v[88:89]
	s_waitcnt lgkmcnt(2)
	v_pk_add_f32 v[36:37], v[36:37], v[94:95]
	v_pk_add_f32 v[34:35], v[34:35], v[92:93]
	s_waitcnt lgkmcnt(1)
	v_pk_add_f32 v[32:33], v[32:33], v[230:231]
	v_pk_add_f32 v[30:31], v[30:31], v[228:229]
	s_waitcnt lgkmcnt(0)
	v_pk_add_f32 v[28:29], v[28:29], v[234:235]
	v_pk_add_f32 v[26:27], v[26:27], v[232:233]
	s_cbranch_scc1 .LBB0_1012
	v_or_b32_e32 v94, s6, v193
	v_ashrrev_i32_e32 v95, 31, v94
	v_lshl_add_u64 v[66:67], v[94:95], 1, s[18:19]
	v_lshl_add_u64 v[68:69], v[66:67], 0, v[0:1]
	global_load_dwordx4 v[198:201], v[68:69], off
	global_load_dwordx4 v[90:93], v[68:69], off offset:64
	v_lshl_add_u64 v[68:69], v[66:67], 0, v[102:103]
	global_load_dwordx4 v[86:89], v[68:69], off
	global_load_dwordx4 v[82:85], v[68:69], off offset:64
	v_lshl_add_u64 v[68:69], v[66:67], 0, v[104:105]
	v_lshl_add_u64 v[66:67], v[66:67], 0, v[106:107]
	global_load_dwordx4 v[78:81], v[68:69], off
	global_load_dwordx4 v[74:77], v[68:69], off offset:64
	global_load_dwordx4 v[70:73], v[66:67], off
	s_nop 0
	global_load_dwordx4 v[66:69], v[66:67], off offset:64
	s_mov_b64 s[8:9], -1
	s_and_b64 vcc, exec, s[28:29]
	s_waitcnt vmcnt(7)
	v_lshlrev_b32_e32 v96, 16, v198
	v_and_b32_e32 v97, 0xffff0000, v198
	v_lshlrev_b32_e32 v198, 16, v199
	v_and_b32_e32 v199, 0xffff0000, v199
	v_lshlrev_b32_e32 v208, 16, v200
	v_and_b32_e32 v209, 0xffff0000, v200
	v_lshlrev_b32_e32 v200, 16, v201
	v_and_b32_e32 v201, 0xffff0000, v201
	v_pk_add_f32 v[52:53], v[52:53], v[198:199]
	v_pk_add_f32 v[50:51], v[50:51], v[96:97]
	v_pk_add_f32 v[48:49], v[48:49], v[200:201]
	v_pk_add_f32 v[46:47], v[46:47], v[208:209]
	v_lshl_add_u64 v[96:97], v[94:95], 1, v[174:175]
	s_cbranch_vccz .LBB0_1015
	v_pk_mul_f32 v[198:199], v[52:53], v[52:53]
	v_pk_mul_f32 v[200:201], v[50:51], v[50:51]
	s_mov_b64 s[8:9], 0
	v_pk_mov_b32 v[208:209], v[200:201], v[198:199] op_sel:[1,0]
	v_mov_b32_e32 v201, v199
	v_pk_add_f32 v[198:199], v[208:209], v[200:201]
	v_pk_mul_f32 v[200:201], v[48:49], v[48:49]
	v_pk_mul_f32 v[208:209], v[46:47], v[46:47]
	v_mov_b32_e32 v210, v200
	v_mov_b32_e32 v211, v208
	v_mov_b32_e32 v208, v201
	v_pk_add_f32 v[200:201], v[210:211], v[208:209]
	v_add_f32_e32 v198, v198, v199
	v_add_f32_e32 v198, v201, v198
	v_add_f32_e32 v210, v200, v198
	v_cvt_pk_bf16_f32 v198, v50, v51
	v_cvt_pk_bf16_f32 v199, v52, v53
	v_cvt_pk_bf16_f32 v200, v46, v47
	v_cvt_pk_bf16_f32 v201, v48, v49
	global_store_dwordx4 v[96:97], v[198:201], off
